# prepass_sample: 30-tap state conv and 15-row pool window loads issued together instead of one serialized round trip each (same arithmetic order)
# speedup vs baseline: 1.0176x; 1.0089x over previous
.LBB0_579:
	s_or_b64 exec, exec, s[76:77]
	v_pk_mul_f32 v[8:9], v[8:9], v[12:13]
	v_readlane_b32 s4, v252, 56
	v_pk_fma_f32 v[6:7], v[6:7], v[10:11], v[8:9]
	v_and_b32_e32 v8, 0xffff0000, v40
	v_pk_fma_f32 v[6:7], v[16:17], v[14:15], v[6:7]
	s_waitcnt lgkmcnt(0)
	s_barrier
	v_mul_f32_e32 v12, v7, v8
	v_lshlrev_b32_e32 v7, 16, v40
	v_mul_f32_e32 v13, v6, v7
	v_mov_b32_e32 v6, s4
	v_readlane_b32 s4, v252, 57
	ds_read2_b32 v[6:7], v6 offset1:1
	v_lshlrev_b32_e32 v14, 16, v39
	v_mov_b32_e32 v8, s4
	ds_read2_b32 v[8:9], v8 offset1:1
	v_readlane_b32 s4, v252, 58
	s_waitcnt lgkmcnt(1)
	v_pk_add_f32 v[6:7], v[6:7], 0 op_sel_hi:[1,0]
	s_lshl_b64 s[38:39], s[38:39], 11
	s_add_u32 s42, s73, s38
	s_waitcnt lgkmcnt(0)
	v_pk_add_f32 v[6:7], v[6:7], v[8:9]
	v_mov_b32_e32 v8, s4
	ds_read2_b32 v[8:9], v8 offset1:1
	v_readlane_b32 s4, v252, 59
	s_addc_u32 s43, s82, s39
	v_lshlrev_b64 v[4:5], 1, v[4:5]
	v_mov_b32_e32 v16, 0xf000
	s_waitcnt lgkmcnt(0)
	v_pk_add_f32 v[6:7], v[6:7], v[8:9]
	v_mov_b32_e32 v8, s4
	ds_read2_b32 v[8:9], v8 offset1:1
	v_readlane_b32 s4, v253, 51
	s_waitcnt lgkmcnt(0)
	v_pk_add_f32 v[6:7], v[6:7], v[8:9]
	v_mov_b32_e32 v8, s4
	ds_read2_b32 v[8:9], v8 offset1:1
	v_readlane_b32 s4, v253, 53
	s_waitcnt lgkmcnt(0)
	v_pk_add_f32 v[6:7], v[6:7], v[8:9]
	v_mov_b32_e32 v8, s4
	ds_read2_b32 v[8:9], v8 offset1:1
	v_readlane_b32 s4, v253, 55
	s_waitcnt lgkmcnt(0)
	v_pk_add_f32 v[6:7], v[6:7], v[8:9]
	v_mov_b32_e32 v8, s4
	ds_read2_b32 v[8:9], v8 offset1:1
	v_readlane_b32 s4, v253, 57
	s_waitcnt lgkmcnt(0)
	v_pk_add_f32 v[6:7], v[6:7], v[8:9]
	v_mov_b32_e32 v8, s4
	ds_read2_b32 v[8:9], v8 offset1:1
	v_readlane_b32 s4, v253, 59
	v_readlane_b32 s5, v253, 60
	s_waitcnt lgkmcnt(0)
	v_pk_add_f32 v[6:7], v[6:7], v[8:9]
	s_nop 0
	v_pk_mul_f32 v[6:7], v[6:7], s[84:85] op_sel_hi:[1,0]
	s_nop 0
	v_fma_f32 v8, -v6, v6, v7
	v_add_f32_e32 v8, 0x358637bd, v8
	v_cmp_gt_f32_e32 vcc, s33, v8
	v_mul_f32_e32 v9, 0x4b800000, v8
	v_pk_add_f32 v[6:7], v[32:33], v[6:7] op_sel_hi:[1,0] neg_lo:[0,1] neg_hi:[0,1]
	v_cndmask_b32_e32 v8, v8, v9, vcc
	v_rsq_f32_e32 v8, v8
	s_nop 0
	v_mul_f32_e32 v9, 0x45800000, v8
	v_cndmask_b32_e32 v8, v8, v9, vcc
	v_pk_mul_f32 v[6:7], v[6:7], v[8:9] op_sel_hi:[1,0]
	v_lshl_add_u64 v[8:9], s[4:5], 0, v[2:3]
	v_readlane_b32 s4, v253, 61
	v_readlane_b32 s5, v253, 62
	global_load_dwordx2 v[8:9], v[8:9], off
	s_nop 0
	v_lshl_add_u64 v[10:11], s[4:5], 0, v[2:3]
	global_load_dwordx2 v[10:11], v[10:11], off
	v_readlane_b32 s4, v253, 63
	v_readlane_b32 s5, v255, 0
	s_waitcnt vmcnt(0)
	v_pk_fma_f32 v[6:7], v[8:9], v[6:7], v[10:11]
	s_nop 0
	v_mul_f32_e32 v8, 0xbfb8aa3b, v6
	v_exp_f32_e32 v8, v8
	s_nop 0
	v_add_f32_e32 v8, 1.0, v8
	v_rcp_f32_e32 v8, v8
	s_nop 0
	v_mul_f32_e32 v10, v6, v8
	v_mul_f32_e32 v6, 0xbfb8aa3b, v7
	v_exp_f32_e32 v6, v6
	s_nop 0
	v_add_f32_e32 v6, 1.0, v6
	v_rcp_f32_e32 v6, v6
	s_nop 0
	v_mul_f32_e32 v11, v7, v6
	v_lshl_add_u64 v[6:7], s[4:5], 0, v[2:3]
	v_readlane_b32 s4, v255, 1
	v_readlane_b32 s5, v255, 2
	global_load_dwordx2 v[6:7], v[6:7], off
	s_nop 0
	v_lshl_add_u64 v[8:9], s[4:5], 0, v[2:3]
	global_load_dwordx2 v[8:9], v[8:9], off
	v_readlane_b32 s4, v253, 0
	v_readlane_b32 s5, v253, 1
	s_waitcnt vmcnt(1)
	v_add_f32_e32 v6, v6, v14
	v_lshlrev_b32_e32 v14, 16, v38
	v_mul_f32_e32 v6, 0xbfb8aa3b, v6
	s_waitcnt vmcnt(0)
	v_add_f32_e32 v8, v8, v14
	v_mul_f32_e32 v8, 0xbfb8aa3b, v8
	v_exp_f32_e32 v8, v8
	v_exp_f32_e32 v6, v6
	v_add_f32_e32 v8, 1.0, v8
	v_add_f32_e32 v6, 1.0, v6
	v_rcp_f32_e32 v8, v8
	v_rcp_f32_e32 v6, v6
	v_mul_f32_e32 v8, v8, v10
	v_fmac_f32_e32 v8, v13, v6
	v_and_b32_e32 v6, 0xffff0000, v39
	v_add_f32_e32 v6, v7, v6
	v_and_b32_e32 v7, 0xffff0000, v38
	v_add_f32_e32 v7, v9, v7
	v_mul_f32_e32 v7, 0xbfb8aa3b, v7
	v_mul_f32_e32 v6, 0xbfb8aa3b, v6
	v_exp_f32_e32 v7, v7
	v_exp_f32_e32 v6, v6
	v_add_f32_e32 v7, 1.0, v7
	v_add_f32_e32 v6, 1.0, v6
	v_rcp_f32_e32 v7, v7
	v_rcp_f32_e32 v6, v6
	v_mul_f32_e32 v7, v7, v11
	v_fmac_f32_e32 v7, v12, v6
	v_cvt_pk_bf16_f32 v8, v8, v7
	v_lshl_add_u64 v[6:7], s[42:43], 0, v[4:5]
	v_lshl_add_u64 v[10:11], s[4:5], 0, v[2:3]
	s_mul_i32 s43, s37, 0xf000
	s_mul_hi_u32 s37, s36, 0xf000
	v_readlane_b32 s4, v252, 2
	s_add_i32 s37, s37, s43
	s_mul_i32 s42, s36, 0xf000
	v_readlane_b32 s18, v252, 16
	v_readlane_b32 s19, v252, 17
	s_add_u32 s44, s18, s42
	v_readlane_b32 s5, v252, 3
	s_addc_u32 s45, s19, s37
	global_store_dword v[6:7], v8, off
	v_lshl_add_u64 v[8:9], s[44:45], 0, v[2:3]
	s_movk_i32 s5, 0x2000
	v_mad_u64_u32 v[10:11], s[44:45], s36, v16, v[10:11]
	v_add_u32_e32 v11, s43, v11
	global_load_dwordx2 v[6:7], v[8:9], off
	s_mov_b32 s45, 0
	s_mov_b32 s44, 0x2000
	v_lshl_add_u64 v[42:43], v[8:9], 0, s[44:45]
	global_load_dwordx2 v[14:15], v[42:43], off offset:-4096
	global_load_dwordx2 v[12:13], v[42:43], off
	s_mov_b32 s44, 0x4000
	v_lshl_add_u64 v[42:43], v[8:9], 0, s[44:45]
	global_load_dwordx2 v[18:19], v[42:43], off offset:-4096
	global_load_dwordx2 v[16:17], v[42:43], off
	s_mov_b32 s44, 0x6000
	v_lshl_add_u64 v[42:43], v[8:9], 0, s[44:45]
	global_load_dwordx2 v[22:23], v[42:43], off offset:-4096
	global_load_dwordx2 v[20:21], v[42:43], off
	s_mov_b32 s44, 0x8000
	v_lshl_add_u64 v[42:43], v[8:9], 0, s[44:45]
	global_load_dwordx2 v[26:27], v[42:43], off offset:-4096
	global_load_dwordx2 v[24:25], v[42:43], off
	s_mov_b32 s44, 0xa000
	v_lshl_add_u64 v[42:43], v[8:9], 0, s[44:45]
	global_load_dwordx2 v[30:31], v[42:43], off offset:-4096
	global_load_dwordx2 v[28:29], v[42:43], off
	s_mov_b32 s44, 0xc000
	v_lshl_add_u64 v[42:43], v[8:9], 0, s[44:45]
	global_load_dwordx2 v[34:35], v[42:43], off offset:-4096
	global_load_dwordx2 v[32:33], v[42:43], off
	s_mov_b32 s44, 0xe000
	v_lshl_add_u64 v[42:43], v[8:9], 0, s[44:45]
	global_load_dwordx2 v[36:37], v[42:43], off offset:-4096
	global_load_dwordx2 v[38:39], v[42:43], off
	v_readlane_b32 s6, v252, 4
	s_movk_i32 s6, 0x4000
	s_movk_i32 s4, 0x6000
	v_readlane_b32 s8, v252, 6
	v_readlane_b32 s9, v252, 7
	v_readlane_b32 s8, v255, 13
	v_readlane_b32 s9, v255, 14
	v_readlane_b32 s7, v252, 5
	s_mul_i32 s7, s96, 0x1e000
	v_readlane_b32 s14, v252, 12
	v_readlane_b32 s15, v252, 13
	v_readlane_b32 s10, v252, 8
	v_readlane_b32 s11, v252, 9
	v_readlane_b32 s12, v252, 10
	v_readlane_b32 s13, v252, 11
	v_readlane_b32 s16, v252, 14
	v_readlane_b32 s17, v252, 15
	v_readlane_b32 s4, v253, 2
	s_add_u32 s36, s4, s42
	v_readlane_b32 s4, v253, 3
	s_addc_u32 s37, s4, s37
	v_lshl_add_u64 v[2:3], s[36:37], 0, v[2:3]
	s_add_u32 s36, s85, s38
	s_addc_u32 s37, s88, s39
	s_add_i32 s50, s50, s96
	s_add_u32 s34, s34, s7
	s_mul_hi_i32 s4, s96, 0x1e000
	s_addc_u32 s35, s35, s4
	s_add_u32 s0, s0, s7
	s_addc_u32 s1, s1, s4
	s_cmpk_gt_i32 s50, 0x7f
	s_waitcnt vmcnt(0)
	s_mov_b32 s44, 0x2000
	v_lshl_add_u64 v[42:43], v[10:11], 0, s[44:45]
	global_store_dwordx2 v[42:43], v[14:15], off offset:-4096
	global_store_dwordx2 v[42:43], v[12:13], off
	s_mov_b32 s44, 0x4000
	v_lshl_add_u64 v[42:43], v[10:11], 0, s[44:45]
	global_store_dwordx2 v[42:43], v[18:19], off offset:-4096
	global_store_dwordx2 v[42:43], v[16:17], off
	s_mov_b32 s44, 0x6000
	v_lshl_add_u64 v[42:43], v[10:11], 0, s[44:45]
	global_store_dwordx2 v[42:43], v[22:23], off offset:-4096
	global_store_dwordx2 v[42:43], v[20:21], off
	s_mov_b32 s44, 0x8000
	v_lshl_add_u64 v[42:43], v[10:11], 0, s[44:45]
	global_store_dwordx2 v[42:43], v[26:27], off offset:-4096
	global_store_dwordx2 v[42:43], v[24:25], off
	s_mov_b32 s44, 0xa000
	v_lshl_add_u64 v[42:43], v[10:11], 0, s[44:45]
	global_store_dwordx2 v[42:43], v[30:31], off offset:-4096
	global_store_dwordx2 v[42:43], v[28:29], off
	s_mov_b32 s44, 0xc000
	v_lshl_add_u64 v[42:43], v[10:11], 0, s[44:45]
	global_store_dwordx2 v[42:43], v[34:35], off offset:-4096
	global_store_dwordx2 v[42:43], v[32:33], off
	s_mov_b32 s44, 0xe000
	v_lshl_add_u64 v[42:43], v[10:11], 0, s[44:45]
	global_store_dwordx2 v[42:43], v[36:37], off offset:-4096
	global_store_dwordx2 v[42:43], v[38:39], off
	v_lshlrev_b32_e32 v8, 16, v0
	v_and_b32_e32 v9, 0xffff0000, v0
	v_pk_add_f32 v[6:7], v[6:7], v[8:9]
	global_store_dwordx2 v[2:3], v[8:9], off
	v_cndmask_b32_e64 v7, v7, v9, s[30:31]
	v_cndmask_b32_e64 v6, v6, v8, s[30:31]
	v_pk_add_f32 v[6:7], v[14:15], v[6:7]
	v_cndmask_b32_e64 v7, v7, v9, s[28:29]
	v_cndmask_b32_e64 v6, v6, v8, s[28:29]
	v_pk_add_f32 v[6:7], v[12:13], v[6:7]
	s_nop 0
	v_cndmask_b32_e64 v7, v7, v9, s[26:27]
	v_cndmask_b32_e64 v6, v6, v8, s[26:27]
	v_pk_add_f32 v[6:7], v[18:19], v[6:7]
	s_nop 0
	v_cndmask_b32_e64 v7, v7, v9, s[24:25]
	v_cndmask_b32_e64 v6, v6, v8, s[24:25]
	v_pk_add_f32 v[6:7], v[16:17], v[6:7]
	s_nop 0
	v_cndmask_b32_e64 v7, v7, v9, s[22:23]
	v_cndmask_b32_e64 v6, v6, v8, s[22:23]
	v_pk_add_f32 v[6:7], v[22:23], v[6:7]
	s_nop 0
	v_cndmask_b32_e64 v7, v7, v9, s[20:21]
	v_cndmask_b32_e64 v6, v6, v8, s[20:21]
	v_pk_add_f32 v[6:7], v[20:21], v[6:7]
	s_nop 0
	v_cndmask_b32_e64 v7, v7, v9, s[8:9]
	v_cndmask_b32_e64 v6, v6, v8, s[8:9]
	v_readlane_b32 s8, v255, 11
	v_pk_add_f32 v[6:7], v[26:27], v[6:7]
	v_readlane_b32 s9, v255, 12
	s_nop 1
	v_cndmask_b32_e64 v7, v7, v9, s[8:9]
	v_cndmask_b32_e64 v6, v6, v8, s[8:9]
	v_readlane_b32 s8, v255, 9
	v_pk_add_f32 v[6:7], v[24:25], v[6:7]
	v_readlane_b32 s9, v255, 10
	s_nop 1
	v_cndmask_b32_e64 v7, v7, v9, s[8:9]
	v_cndmask_b32_e64 v6, v6, v8, s[8:9]
	v_readlane_b32 s8, v255, 7
	v_pk_add_f32 v[6:7], v[30:31], v[6:7]
	v_readlane_b32 s9, v255, 8
	s_nop 1
	v_cndmask_b32_e64 v7, v7, v9, s[8:9]
	v_cndmask_b32_e64 v6, v6, v8, s[8:9]
	v_pk_add_f32 v[6:7], v[28:29], v[6:7]
	v_readlane_b32 s8, v255, 5
	v_cndmask_b32_e64 v7, v7, v9, s[2:3]
	v_cndmask_b32_e64 v6, v6, v8, s[2:3]
	v_pk_add_f32 v[6:7], v[34:35], v[6:7]
	v_readlane_b32 s9, v255, 6
	v_cndmask_b32_e64 v7, v7, v9, s[78:79]
	v_cndmask_b32_e64 v6, v6, v8, s[78:79]
	v_pk_add_f32 v[6:7], v[32:33], v[6:7]
	s_nop 0
	v_cndmask_b32_e64 v7, v7, v9, s[46:47]
	v_cndmask_b32_e64 v6, v6, v8, s[46:47]
	v_pk_add_f32 v[6:7], v[36:37], v[6:7]
	s_nop 0
	v_cndmask_b32_e64 v7, v7, v9, s[8:9]
	v_cndmask_b32_e64 v6, v6, v8, s[8:9]
	v_readlane_b32 s8, v255, 3
	v_pk_add_f32 v[6:7], v[38:39], v[6:7]
	v_readlane_b32 s9, v255, 4
	s_nop 1
	v_cndmask_b32_e64 v0, v7, v9, s[8:9]
	v_cndmask_b32_e64 v6, v6, v8, s[8:9]
	v_fma_f32 v2, v161, v6, -v8
	v_fma_f32 v0, v161, v0, -v9
	v_cvt_pk_bf16_f32 v0, v2, v0
	v_lshl_add_u64 v[2:3], s[36:37], 0, v[4:5]
	global_store_dword v[2:3], v0, off
	s_waitcnt lgkmcnt(0)
	s_barrier
	s_cbranch_scc1 .LBB0_570

.LBB0_582:
	s_mov_b32 s45, 0
	s_mov_b32 s44, 0x1000
	v_lshl_add_u64 v[42:43], v[24:25], 0, s[44:45]
	global_load_dwordx2 v[44:45], v[42:43], off offset:-4096
	global_load_dwordx2 v[46:47], v[42:43], off
	v_lshl_add_u64 v[42:43], v[20:21], 0, s[44:45]
	global_load_dwordx2 v[104:105], v[42:43], off offset:-4096
	global_load_dwordx2 v[106:107], v[42:43], off
	s_mov_b32 s44, 0x3000
	v_lshl_add_u64 v[42:43], v[24:25], 0, s[44:45]
	global_load_dwordx2 v[48:49], v[42:43], off offset:-4096
	global_load_dwordx2 v[50:51], v[42:43], off
	v_lshl_add_u64 v[42:43], v[20:21], 0, s[44:45]
	global_load_dwordx2 v[108:109], v[42:43], off offset:-4096
	global_load_dwordx2 v[110:111], v[42:43], off
	s_mov_b32 s44, 0x5000
	v_lshl_add_u64 v[42:43], v[24:25], 0, s[44:45]
	global_load_dwordx2 v[52:53], v[42:43], off offset:-4096
	global_load_dwordx2 v[54:55], v[42:43], off
	v_lshl_add_u64 v[42:43], v[20:21], 0, s[44:45]
	global_load_dwordx2 v[112:113], v[42:43], off offset:-4096
	global_load_dwordx2 v[114:115], v[42:43], off
	s_mov_b32 s44, 0x7000
	v_lshl_add_u64 v[42:43], v[24:25], 0, s[44:45]
	global_load_dwordx2 v[56:57], v[42:43], off offset:-4096
	global_load_dwordx2 v[58:59], v[42:43], off
	v_lshl_add_u64 v[42:43], v[20:21], 0, s[44:45]
	global_load_dwordx2 v[116:117], v[42:43], off offset:-4096
	global_load_dwordx2 v[118:119], v[42:43], off
	s_mov_b32 s44, 0x9000
	v_lshl_add_u64 v[42:43], v[24:25], 0, s[44:45]
	global_load_dwordx2 v[60:61], v[42:43], off offset:-4096
	global_load_dwordx2 v[62:63], v[42:43], off
	v_lshl_add_u64 v[42:43], v[20:21], 0, s[44:45]
	global_load_dwordx2 v[120:121], v[42:43], off offset:-4096
	global_load_dwordx2 v[122:123], v[42:43], off
	s_mov_b32 s44, 0xb000
	v_lshl_add_u64 v[42:43], v[24:25], 0, s[44:45]
	global_load_dwordx2 v[64:65], v[42:43], off offset:-4096
	global_load_dwordx2 v[66:67], v[42:43], off
	v_lshl_add_u64 v[42:43], v[20:21], 0, s[44:45]
	global_load_dwordx2 v[124:125], v[42:43], off offset:-4096
	global_load_dwordx2 v[126:127], v[42:43], off
	s_mov_b32 s44, 0xd000
	v_lshl_add_u64 v[42:43], v[24:25], 0, s[44:45]
	global_load_dwordx2 v[68:69], v[42:43], off offset:-4096
	global_load_dwordx2 v[70:71], v[42:43], off
	v_lshl_add_u64 v[42:43], v[20:21], 0, s[44:45]
	global_load_dwordx2 v[128:129], v[42:43], off offset:-4096
	global_load_dwordx2 v[130:131], v[42:43], off
	s_mov_b32 s44, 0xf000
	v_lshl_add_u64 v[42:43], v[24:25], 0, s[44:45]
	global_load_dwordx2 v[72:73], v[42:43], off offset:-4096
	global_load_dwordx2 v[74:75], v[42:43], off
	v_lshl_add_u64 v[42:43], v[20:21], 0, s[44:45]
	global_load_dwordx2 v[132:133], v[42:43], off offset:-4096
	global_load_dwordx2 v[134:135], v[42:43], off
	s_mov_b32 s44, 0x11000
	v_lshl_add_u64 v[42:43], v[24:25], 0, s[44:45]
	global_load_dwordx2 v[76:77], v[42:43], off offset:-4096
	global_load_dwordx2 v[78:79], v[42:43], off
	v_lshl_add_u64 v[42:43], v[20:21], 0, s[44:45]
	global_load_dwordx2 v[136:137], v[42:43], off offset:-4096
	global_load_dwordx2 v[138:139], v[42:43], off
	s_mov_b32 s44, 0x13000
	v_lshl_add_u64 v[42:43], v[24:25], 0, s[44:45]
	global_load_dwordx2 v[80:81], v[42:43], off offset:-4096
	global_load_dwordx2 v[82:83], v[42:43], off
	v_lshl_add_u64 v[42:43], v[20:21], 0, s[44:45]
	global_load_dwordx2 v[140:141], v[42:43], off offset:-4096
	global_load_dwordx2 v[142:143], v[42:43], off
	s_mov_b32 s44, 0x15000
	v_lshl_add_u64 v[42:43], v[24:25], 0, s[44:45]
	global_load_dwordx2 v[84:85], v[42:43], off offset:-4096
	global_load_dwordx2 v[86:87], v[42:43], off
	v_lshl_add_u64 v[42:43], v[20:21], 0, s[44:45]
	global_load_dwordx2 v[144:145], v[42:43], off offset:-4096
	global_load_dwordx2 v[146:147], v[42:43], off
	s_mov_b32 s44, 0x17000
	v_lshl_add_u64 v[42:43], v[24:25], 0, s[44:45]
	global_load_dwordx2 v[88:89], v[42:43], off offset:-4096
	global_load_dwordx2 v[90:91], v[42:43], off
	v_lshl_add_u64 v[42:43], v[20:21], 0, s[44:45]
	global_load_dwordx2 v[148:149], v[42:43], off offset:-4096
	global_load_dwordx2 v[150:151], v[42:43], off
	s_mov_b32 s44, 0x19000
	v_lshl_add_u64 v[42:43], v[24:25], 0, s[44:45]
	global_load_dwordx2 v[92:93], v[42:43], off offset:-4096
	global_load_dwordx2 v[94:95], v[42:43], off
	v_lshl_add_u64 v[42:43], v[20:21], 0, s[44:45]
	global_load_dwordx2 v[152:153], v[42:43], off offset:-4096
	global_load_dwordx2 v[154:155], v[42:43], off
	s_mov_b32 s44, 0x1b000
	v_lshl_add_u64 v[42:43], v[24:25], 0, s[44:45]
	global_load_dwordx2 v[96:97], v[42:43], off offset:-4096
	global_load_dwordx2 v[98:99], v[42:43], off
	v_lshl_add_u64 v[42:43], v[20:21], 0, s[44:45]
	global_load_dwordx2 v[156:157], v[42:43], off offset:-4096
	global_load_dwordx2 v[158:159], v[42:43], off
	s_mov_b32 s44, 0x1d000
	v_lshl_add_u64 v[42:43], v[24:25], 0, s[44:45]
	global_load_dwordx2 v[100:101], v[42:43], off offset:-4096
	global_load_dwordx2 v[102:103], v[42:43], off
	v_lshl_add_u64 v[42:43], v[20:21], 0, s[44:45]
	global_load_dwordx2 v[34:35], v[42:43], off offset:-4096
	global_load_dwordx2 v[36:37], v[42:43], off
	s_waitcnt vmcnt(57)
	v_pk_fma_f32 v[32:33], v[44:45], v[104:105], v[32:33]
	s_waitcnt vmcnt(56)
	v_pk_fma_f32 v[32:33], v[46:47], v[106:107], v[32:33]
	s_mov_b32 s44, 0x6570000
	v_lshl_add_u64 v[42:43], v[22:23], 0, s[44:45]
	global_store_dwordx2 v[42:43], v[46:47], off
	s_waitcnt vmcnt(54)
	v_pk_fma_f32 v[32:33], v[48:49], v[108:109], v[32:33]
	s_mov_b32 s44, 0x6571000
	v_lshl_add_u64 v[42:43], v[22:23], 0, s[44:45]
	global_store_dwordx2 v[42:43], v[48:49], off
	s_waitcnt vmcnt(54)
	v_pk_fma_f32 v[32:33], v[50:51], v[110:111], v[32:33]
	s_mov_b32 s44, 0x6572000
	v_lshl_add_u64 v[42:43], v[22:23], 0, s[44:45]
	global_store_dwordx2 v[42:43], v[50:51], off
	s_waitcnt vmcnt(52)
	v_pk_fma_f32 v[32:33], v[52:53], v[112:113], v[32:33]
	s_mov_b32 s44, 0x6573000
	v_lshl_add_u64 v[42:43], v[22:23], 0, s[44:45]
	global_store_dwordx2 v[42:43], v[52:53], off
	s_waitcnt vmcnt(52)
	v_pk_fma_f32 v[32:33], v[54:55], v[114:115], v[32:33]
	s_mov_b32 s44, 0x6574000
	v_lshl_add_u64 v[42:43], v[22:23], 0, s[44:45]
	global_store_dwordx2 v[42:43], v[54:55], off
	s_waitcnt vmcnt(50)
	v_pk_fma_f32 v[32:33], v[56:57], v[116:117], v[32:33]
	s_mov_b32 s44, 0x6575000
	v_lshl_add_u64 v[42:43], v[22:23], 0, s[44:45]
	global_store_dwordx2 v[42:43], v[56:57], off
	s_waitcnt vmcnt(50)
	v_pk_fma_f32 v[32:33], v[58:59], v[118:119], v[32:33]
	s_mov_b32 s44, 0x6576000
	v_lshl_add_u64 v[42:43], v[22:23], 0, s[44:45]
	global_store_dwordx2 v[42:43], v[58:59], off
	s_waitcnt vmcnt(48)
	v_pk_fma_f32 v[32:33], v[60:61], v[120:121], v[32:33]
	s_mov_b32 s44, 0x6577000
	v_lshl_add_u64 v[42:43], v[22:23], 0, s[44:45]
	global_store_dwordx2 v[42:43], v[60:61], off
	s_waitcnt vmcnt(48)
	v_pk_fma_f32 v[32:33], v[62:63], v[122:123], v[32:33]
	s_mov_b32 s44, 0x6578000
	v_lshl_add_u64 v[42:43], v[22:23], 0, s[44:45]
	global_store_dwordx2 v[42:43], v[62:63], off
	s_waitcnt vmcnt(46)
	v_pk_fma_f32 v[32:33], v[64:65], v[124:125], v[32:33]
	s_mov_b32 s44, 0x6579000
	v_lshl_add_u64 v[42:43], v[22:23], 0, s[44:45]
	global_store_dwordx2 v[42:43], v[64:65], off
	s_waitcnt vmcnt(46)
	v_pk_fma_f32 v[32:33], v[66:67], v[126:127], v[32:33]
	s_mov_b32 s44, 0x657a000
	v_lshl_add_u64 v[42:43], v[22:23], 0, s[44:45]
	global_store_dwordx2 v[42:43], v[66:67], off
	s_waitcnt vmcnt(44)
	v_pk_fma_f32 v[32:33], v[68:69], v[128:129], v[32:33]
	s_mov_b32 s44, 0x657b000
	v_lshl_add_u64 v[42:43], v[22:23], 0, s[44:45]
	global_store_dwordx2 v[42:43], v[68:69], off
	s_waitcnt vmcnt(44)
	v_pk_fma_f32 v[32:33], v[70:71], v[130:131], v[32:33]
	s_mov_b32 s44, 0x657c000
	v_lshl_add_u64 v[42:43], v[22:23], 0, s[44:45]
	global_store_dwordx2 v[42:43], v[70:71], off
	s_waitcnt vmcnt(42)
	v_pk_fma_f32 v[32:33], v[72:73], v[132:133], v[32:33]
	s_mov_b32 s44, 0x657d000
	v_lshl_add_u64 v[42:43], v[22:23], 0, s[44:45]
	global_store_dwordx2 v[42:43], v[72:73], off
	s_waitcnt vmcnt(42)
	v_pk_fma_f32 v[32:33], v[74:75], v[134:135], v[32:33]
	s_mov_b32 s44, 0x657e000
	v_lshl_add_u64 v[42:43], v[22:23], 0, s[44:45]
	global_store_dwordx2 v[42:43], v[74:75], off
	s_waitcnt vmcnt(40)
	v_pk_fma_f32 v[32:33], v[76:77], v[136:137], v[32:33]
	s_mov_b32 s44, 0x657f000
	v_lshl_add_u64 v[42:43], v[22:23], 0, s[44:45]
	global_store_dwordx2 v[42:43], v[76:77], off
	s_waitcnt vmcnt(40)
	v_pk_fma_f32 v[32:33], v[78:79], v[138:139], v[32:33]
	s_mov_b32 s44, 0x6580000
	v_lshl_add_u64 v[42:43], v[22:23], 0, s[44:45]
	global_store_dwordx2 v[42:43], v[78:79], off
	s_waitcnt vmcnt(38)
	v_pk_fma_f32 v[32:33], v[80:81], v[140:141], v[32:33]
	s_mov_b32 s44, 0x6581000
	v_lshl_add_u64 v[42:43], v[22:23], 0, s[44:45]
	global_store_dwordx2 v[42:43], v[80:81], off
	s_waitcnt vmcnt(38)
	v_pk_fma_f32 v[32:33], v[82:83], v[142:143], v[32:33]
	s_mov_b32 s44, 0x6582000
	v_lshl_add_u64 v[42:43], v[22:23], 0, s[44:45]
	global_store_dwordx2 v[42:43], v[82:83], off
	s_waitcnt vmcnt(36)
	v_pk_fma_f32 v[32:33], v[84:85], v[144:145], v[32:33]
	s_mov_b32 s44, 0x6583000
	v_lshl_add_u64 v[42:43], v[22:23], 0, s[44:45]
	global_store_dwordx2 v[42:43], v[84:85], off
	s_waitcnt vmcnt(36)
	v_pk_fma_f32 v[32:33], v[86:87], v[146:147], v[32:33]
	s_mov_b32 s44, 0x6584000
	v_lshl_add_u64 v[42:43], v[22:23], 0, s[44:45]
	global_store_dwordx2 v[42:43], v[86:87], off
	s_waitcnt vmcnt(34)
	v_pk_fma_f32 v[32:33], v[88:89], v[148:149], v[32:33]
	s_mov_b32 s44, 0x6585000
	v_lshl_add_u64 v[42:43], v[22:23], 0, s[44:45]
	global_store_dwordx2 v[42:43], v[88:89], off
	s_waitcnt vmcnt(34)
	v_pk_fma_f32 v[32:33], v[90:91], v[150:151], v[32:33]
	s_mov_b32 s44, 0x6586000
	v_lshl_add_u64 v[42:43], v[22:23], 0, s[44:45]
	global_store_dwordx2 v[42:43], v[90:91], off
	s_waitcnt vmcnt(32)
	v_pk_fma_f32 v[32:33], v[92:93], v[152:153], v[32:33]
	s_mov_b32 s44, 0x6587000
	v_lshl_add_u64 v[42:43], v[22:23], 0, s[44:45]
	global_store_dwordx2 v[42:43], v[92:93], off
	s_waitcnt vmcnt(32)
	v_pk_fma_f32 v[32:33], v[94:95], v[154:155], v[32:33]
	s_mov_b32 s44, 0x6588000
	v_lshl_add_u64 v[42:43], v[22:23], 0, s[44:45]
	global_store_dwordx2 v[42:43], v[94:95], off
	s_waitcnt vmcnt(30)
	v_pk_fma_f32 v[32:33], v[96:97], v[156:157], v[32:33]
	s_mov_b32 s44, 0x6589000
	v_lshl_add_u64 v[42:43], v[22:23], 0, s[44:45]
	global_store_dwordx2 v[42:43], v[96:97], off
	s_waitcnt vmcnt(30)
	v_pk_fma_f32 v[32:33], v[98:99], v[158:159], v[32:33]
	s_mov_b32 s44, 0x658a000
	v_lshl_add_u64 v[42:43], v[22:23], 0, s[44:45]
	global_store_dwordx2 v[42:43], v[98:99], off
	s_waitcnt vmcnt(28)
	v_pk_fma_f32 v[32:33], v[100:101], v[34:35], v[32:33]
	s_mov_b32 s44, 0x658b000
	v_lshl_add_u64 v[42:43], v[22:23], 0, s[44:45]
	global_store_dwordx2 v[42:43], v[100:101], off
	s_waitcnt vmcnt(28)
	v_pk_fma_f32 v[32:33], v[102:103], v[36:37], v[32:33]
	s_mov_b32 s44, 0x658c000
	v_lshl_add_u64 v[42:43], v[22:23], 0, s[44:45]
	global_store_dwordx2 v[42:43], v[102:103], off
	s_branch .LBB0_584
